# seams 3 and 9 (after the K-split fix-up passes) replaced by a dependency counter: fix-up stores write-through + signal; only units of row tile 32 in the next GEMM wait on it
# speedup vs baseline: 1.0139x; 1.0083x over previous
; __device__ __forceinline__ float bf_lo(unsigned w) { return __uint_as_float(w << 16); }
; __device__ __forceinline__ float bf_hi(unsigned w) { return __uint_as_float(w & 0xffff0000u); }
; template <int MODE> __device__ __forceinline__ void fix_resid(const float* part, int nsl, const float* xp, const float* xs, const float* meta, float* xbuf, bf16_t* xb, float* ss, float* out, int gw, int ngw, int lane) {
;     for (int it = gw; it < NTAIL * 8; it += ngw) {
;         const int rloc = it >> 3, row = TAIL0 + rloc, col = (it & 7) * 256 + lane * 4;
;         const bf16_t* p = (const bf16_t*)part + (size_t)rloc * 2048 + col;
;         f32x4_t v = (f32x4_t){0.f, 0.f, 0.f, 0.f};
; #pragma unroll 8
;         for (int s = 0; s < nsl; ++s) { const u32x2_t w = __builtin_nontemporal_load((const u32x2_t*)(p + (size_t)s * (256 * 2048))); v += (f32x4_t){bf_lo(w.x), bf_hi(w.x), bf_lo(w.y), bf_hi(w.y)}; }
.LBB0_445:
	s_lshl_b32 s6, s2, 1
	s_and_b32 s6, s6, 0xe00
	v_lshl_or_b32 v0, v241, 1, s6
	s_ashr_i32 s6, s14, 3
	s_ashr_i32 s7, s6, 31
	s_lshl_b64 s[18:19], s[6:7], 12
	s_add_u32 s18, s86, s18
	s_addc_u32 s19, s87, s19
	s_waitcnt lgkmcnt(0)
	v_mov_b32_e32 v6, 0
	v_mov_b32_e32 v7, v1
	v_mov_b32_e32 v8, 0
	v_mov_b32_e32 v9, v1
	global_load_dwordx2 v[32:33], v0, s[18:19] nt
	s_add_u32 s18, s18, 0x100000
	s_addc_u32 s19, s19, 0
	global_load_dwordx2 v[34:35], v0, s[18:19] nt
	s_add_u32 s18, s18, 0x100000
	s_addc_u32 s19, s19, 0
	global_load_dwordx2 v[36:37], v0, s[18:19] nt
	s_add_u32 s18, s18, 0x100000
	s_addc_u32 s19, s19, 0
	global_load_dwordx2 v[38:39], v0, s[18:19] nt
	s_add_u32 s18, s18, 0x100000
	s_addc_u32 s19, s19, 0
	global_load_dwordx2 v[40:41], v0, s[18:19] nt
	s_add_u32 s18, s18, 0x100000
	s_addc_u32 s19, s19, 0
	global_load_dwordx2 v[42:43], v0, s[18:19] nt
	s_add_u32 s18, s18, 0x100000
	s_addc_u32 s19, s19, 0
	global_load_dwordx2 v[44:45], v0, s[18:19] nt
	s_add_u32 s18, s18, 0x100000
	s_addc_u32 s19, s19, 0
	global_load_dwordx2 v[46:47], v0, s[18:19] nt
	s_add_u32 s18, s18, 0x100000
	s_addc_u32 s19, s19, 0
	global_load_dwordx2 v[48:49], v0, s[18:19] nt
	s_add_u32 s18, s18, 0x100000
	s_addc_u32 s19, s19, 0
	global_load_dwordx2 v[50:51], v0, s[18:19] nt
	s_add_u32 s18, s18, 0x100000
	s_addc_u32 s19, s19, 0
	global_load_dwordx2 v[52:53], v0, s[18:19] nt
	s_add_u32 s18, s18, 0x100000
	s_addc_u32 s19, s19, 0
	global_load_dwordx2 v[54:55], v0, s[18:19] nt
	s_add_u32 s18, s18, 0x100000
	s_addc_u32 s19, s19, 0
	global_load_dwordx2 v[56:57], v0, s[18:19] nt
	s_add_u32 s18, s18, 0x100000
	s_addc_u32 s19, s19, 0
	global_load_dwordx2 v[58:59], v0, s[18:19] nt
	s_add_u32 s18, s18, 0x100000
	s_addc_u32 s19, s19, 0
	global_load_dwordx2 v[60:61], v0, s[18:19] nt
	s_add_u32 s18, s18, 0x100000
	s_addc_u32 s19, s19, 0
	global_load_dwordx2 v[62:63], v0, s[18:19] nt
	s_add_u32 s18, s18, 0x100000
	s_addc_u32 s19, s19, 0
	global_load_dwordx2 v[64:65], v0, s[18:19] nt
	s_add_u32 s18, s18, 0x100000
	s_addc_u32 s19, s19, 0
	global_load_dwordx2 v[66:67], v0, s[18:19] nt
	s_add_u32 s18, s18, 0x100000
	s_addc_u32 s19, s19, 0
	global_load_dwordx2 v[68:69], v0, s[18:19] nt
	s_add_u32 s18, s18, 0x100000
	s_addc_u32 s19, s19, 0
	global_load_dwordx2 v[70:71], v0, s[18:19] nt
	s_add_u32 s18, s18, 0x100000
	s_addc_u32 s19, s19, 0
	global_load_dwordx2 v[72:73], v0, s[18:19] nt
	s_add_u32 s18, s18, 0x100000
	s_addc_u32 s19, s19, 0
	global_load_dwordx2 v[74:75], v0, s[18:19] nt
	s_add_u32 s18, s18, 0x100000
	s_addc_u32 s19, s19, 0
	global_load_dwordx2 v[76:77], v0, s[18:19] nt
	s_add_u32 s18, s18, 0x100000
	s_addc_u32 s19, s19, 0
	global_load_dwordx2 v[78:79], v0, s[18:19] nt
	s_add_u32 s18, s18, 0x100000
	s_addc_u32 s19, s19, 0
	global_load_dwordx2 v[80:81], v0, s[18:19] nt
	s_add_u32 s18, s18, 0x100000
	s_addc_u32 s19, s19, 0
	global_load_dwordx2 v[82:83], v0, s[18:19] nt
	s_add_u32 s18, s18, 0x100000
	s_addc_u32 s19, s19, 0
	global_load_dwordx2 v[84:85], v0, s[18:19] nt
	s_add_u32 s18, s18, 0x100000
	s_addc_u32 s19, s19, 0
	global_load_dwordx2 v[86:87], v0, s[18:19] nt
	s_add_u32 s18, s18, 0x100000
	s_addc_u32 s19, s19, 0
	global_load_dwordx2 v[88:89], v0, s[18:19] nt
	s_add_u32 s18, s18, 0x100000
	s_addc_u32 s19, s19, 0
	global_load_dwordx2 v[90:91], v0, s[18:19] nt
	s_add_u32 s18, s18, 0x100000
	s_addc_u32 s19, s19, 0
	global_load_dwordx2 v[92:93], v0, s[18:19] nt
	s_add_u32 s18, s18, 0x100000
	s_addc_u32 s19, s19, 0
	global_load_dwordx2 v[94:95], v0, s[18:19] nt
	s_waitcnt vmcnt(24)
	v_lshlrev_b32_e32 v20, 16, v32
	v_and_b32_e32 v21, 0xffff0000, v32
	v_lshlrev_b32_e32 v18, 16, v33
	v_and_b32_e32 v19, 0xffff0000, v33
	v_pk_add_f32 v[8:9], v[8:9], v[18:19]
	v_pk_add_f32 v[6:7], v[6:7], v[20:21]
	v_lshlrev_b32_e32 v20, 16, v34
	v_and_b32_e32 v21, 0xffff0000, v34
	v_lshlrev_b32_e32 v18, 16, v35
	v_and_b32_e32 v19, 0xffff0000, v35
	v_pk_add_f32 v[8:9], v[8:9], v[18:19]
	v_pk_add_f32 v[6:7], v[6:7], v[20:21]
	v_lshlrev_b32_e32 v20, 16, v36
	v_and_b32_e32 v21, 0xffff0000, v36
	v_lshlrev_b32_e32 v18, 16, v37
	v_and_b32_e32 v19, 0xffff0000, v37
	v_pk_add_f32 v[8:9], v[8:9], v[18:19]
	v_pk_add_f32 v[6:7], v[6:7], v[20:21]
	v_lshlrev_b32_e32 v20, 16, v38
	v_and_b32_e32 v21, 0xffff0000, v38
	v_lshlrev_b32_e32 v18, 16, v39
	v_and_b32_e32 v19, 0xffff0000, v39
	v_pk_add_f32 v[8:9], v[8:9], v[18:19]
	v_pk_add_f32 v[6:7], v[6:7], v[20:21]
	v_lshlrev_b32_e32 v20, 16, v40
	v_and_b32_e32 v21, 0xffff0000, v40
	v_lshlrev_b32_e32 v18, 16, v41
	v_and_b32_e32 v19, 0xffff0000, v41
	v_pk_add_f32 v[8:9], v[8:9], v[18:19]
	v_pk_add_f32 v[6:7], v[6:7], v[20:21]
	v_lshlrev_b32_e32 v20, 16, v42
	v_and_b32_e32 v21, 0xffff0000, v42
	v_lshlrev_b32_e32 v18, 16, v43
	v_and_b32_e32 v19, 0xffff0000, v43
	v_pk_add_f32 v[8:9], v[8:9], v[18:19]
	v_pk_add_f32 v[6:7], v[6:7], v[20:21]
	v_lshlrev_b32_e32 v20, 16, v44
	v_and_b32_e32 v21, 0xffff0000, v44
	v_lshlrev_b32_e32 v18, 16, v45
	v_and_b32_e32 v19, 0xffff0000, v45
	v_pk_add_f32 v[8:9], v[8:9], v[18:19]
	v_pk_add_f32 v[6:7], v[6:7], v[20:21]
	v_lshlrev_b32_e32 v20, 16, v46
	v_and_b32_e32 v21, 0xffff0000, v46
	v_lshlrev_b32_e32 v18, 16, v47
	v_and_b32_e32 v19, 0xffff0000, v47
	v_pk_add_f32 v[8:9], v[8:9], v[18:19]
	v_pk_add_f32 v[6:7], v[6:7], v[20:21]
	s_waitcnt vmcnt(16)
; __device__ __forceinline__ float bf_lo(unsigned w) { return __uint_as_float(w << 16); }
; __device__ __forceinline__ float bf_hi(unsigned w) { return __uint_as_float(w & 0xffff0000u); }
; template <int MODE> __device__ __forceinline__ void fix_resid(const float* part, int nsl, const float* xp, const float* xs, const float* meta, float* xbuf, bf16_t* xb, float* ss, float* out, int gw, int ngw, int lane) {
;     for (int it = gw; it < NTAIL * 8; it += ngw) {
;         const int rloc = it >> 3, row = TAIL0 + rloc, col = (it & 7) * 256 + lane * 4;
;         const bf16_t* p = (const bf16_t*)part + (size_t)rloc * 2048 + col;
;         f32x4_t v = (f32x4_t){0.f, 0.f, 0.f, 0.f};
; #pragma unroll 8
;         for (int s = 0; s < nsl; ++s) { const u32x2_t w = __builtin_nontemporal_load((const u32x2_t*)(p + (size_t)s * (256 * 2048))); v += (f32x4_t){bf_lo(w.x), bf_hi(w.x), bf_lo(w.y), bf_hi(w.y)}; }
;         const float scale = (MODE == 1) ? 1.0f : 0.5f;
	v_lshlrev_b32_e32 v20, 16, v48
	v_and_b32_e32 v21, 0xffff0000, v48
	v_lshlrev_b32_e32 v18, 16, v49
	v_and_b32_e32 v19, 0xffff0000, v49
	v_pk_add_f32 v[8:9], v[8:9], v[18:19]
	v_pk_add_f32 v[6:7], v[6:7], v[20:21]
	v_lshlrev_b32_e32 v20, 16, v50
	v_and_b32_e32 v21, 0xffff0000, v50
	v_lshlrev_b32_e32 v18, 16, v51
	v_and_b32_e32 v19, 0xffff0000, v51
	v_pk_add_f32 v[8:9], v[8:9], v[18:19]
	v_pk_add_f32 v[6:7], v[6:7], v[20:21]
	v_lshlrev_b32_e32 v20, 16, v52
	v_and_b32_e32 v21, 0xffff0000, v52
	v_lshlrev_b32_e32 v18, 16, v53
	v_and_b32_e32 v19, 0xffff0000, v53
	v_pk_add_f32 v[8:9], v[8:9], v[18:19]
	v_pk_add_f32 v[6:7], v[6:7], v[20:21]
	v_lshlrev_b32_e32 v20, 16, v54
	v_and_b32_e32 v21, 0xffff0000, v54
	v_lshlrev_b32_e32 v18, 16, v55
	v_and_b32_e32 v19, 0xffff0000, v55
	v_pk_add_f32 v[8:9], v[8:9], v[18:19]
	v_pk_add_f32 v[6:7], v[6:7], v[20:21]
	v_lshlrev_b32_e32 v20, 16, v56
	v_and_b32_e32 v21, 0xffff0000, v56
	v_lshlrev_b32_e32 v18, 16, v57
	v_and_b32_e32 v19, 0xffff0000, v57
	v_pk_add_f32 v[8:9], v[8:9], v[18:19]
	v_pk_add_f32 v[6:7], v[6:7], v[20:21]
	v_lshlrev_b32_e32 v20, 16, v58
	v_and_b32_e32 v21, 0xffff0000, v58
	v_lshlrev_b32_e32 v18, 16, v59
	v_and_b32_e32 v19, 0xffff0000, v59
	v_pk_add_f32 v[8:9], v[8:9], v[18:19]
	v_pk_add_f32 v[6:7], v[6:7], v[20:21]
	v_lshlrev_b32_e32 v20, 16, v60
	v_and_b32_e32 v21, 0xffff0000, v60
	v_lshlrev_b32_e32 v18, 16, v61
	v_and_b32_e32 v19, 0xffff0000, v61
	v_pk_add_f32 v[8:9], v[8:9], v[18:19]
	v_pk_add_f32 v[6:7], v[6:7], v[20:21]
	v_lshlrev_b32_e32 v20, 16, v62
	v_and_b32_e32 v21, 0xffff0000, v62
	v_lshlrev_b32_e32 v18, 16, v63
	v_and_b32_e32 v19, 0xffff0000, v63
	v_pk_add_f32 v[8:9], v[8:9], v[18:19]
	v_pk_add_f32 v[6:7], v[6:7], v[20:21]
	s_waitcnt vmcnt(8)
	v_lshlrev_b32_e32 v20, 16, v64
	v_and_b32_e32 v21, 0xffff0000, v64
	v_lshlrev_b32_e32 v18, 16, v65
	v_and_b32_e32 v19, 0xffff0000, v65
	v_pk_add_f32 v[8:9], v[8:9], v[18:19]
	v_pk_add_f32 v[6:7], v[6:7], v[20:21]
	v_lshlrev_b32_e32 v20, 16, v66
	v_and_b32_e32 v21, 0xffff0000, v66
	v_lshlrev_b32_e32 v18, 16, v67
	v_and_b32_e32 v19, 0xffff0000, v67
	v_pk_add_f32 v[8:9], v[8:9], v[18:19]
	v_pk_add_f32 v[6:7], v[6:7], v[20:21]
	v_lshlrev_b32_e32 v20, 16, v68
	v_and_b32_e32 v21, 0xffff0000, v68
	v_lshlrev_b32_e32 v18, 16, v69
	v_and_b32_e32 v19, 0xffff0000, v69
	v_pk_add_f32 v[8:9], v[8:9], v[18:19]
	v_pk_add_f32 v[6:7], v[6:7], v[20:21]
	v_lshlrev_b32_e32 v20, 16, v70
	v_and_b32_e32 v21, 0xffff0000, v70
	v_lshlrev_b32_e32 v18, 16, v71
	v_and_b32_e32 v19, 0xffff0000, v71
	v_pk_add_f32 v[8:9], v[8:9], v[18:19]
	v_pk_add_f32 v[6:7], v[6:7], v[20:21]
	v_lshlrev_b32_e32 v20, 16, v72
	v_and_b32_e32 v21, 0xffff0000, v72
	v_lshlrev_b32_e32 v18, 16, v73
	v_and_b32_e32 v19, 0xffff0000, v73
	v_pk_add_f32 v[8:9], v[8:9], v[18:19]
	v_pk_add_f32 v[6:7], v[6:7], v[20:21]
	v_lshlrev_b32_e32 v20, 16, v74
	v_and_b32_e32 v21, 0xffff0000, v74
	v_lshlrev_b32_e32 v18, 16, v75
	v_and_b32_e32 v19, 0xffff0000, v75
	v_pk_add_f32 v[8:9], v[8:9], v[18:19]
	v_pk_add_f32 v[6:7], v[6:7], v[20:21]
	v_lshlrev_b32_e32 v20, 16, v76
	v_and_b32_e32 v21, 0xffff0000, v76
	v_lshlrev_b32_e32 v18, 16, v77
	v_and_b32_e32 v19, 0xffff0000, v77
	v_pk_add_f32 v[8:9], v[8:9], v[18:19]
	v_pk_add_f32 v[6:7], v[6:7], v[20:21]
	v_lshlrev_b32_e32 v20, 16, v78
	v_and_b32_e32 v21, 0xffff0000, v78
	v_lshlrev_b32_e32 v18, 16, v79
	v_and_b32_e32 v19, 0xffff0000, v79
	v_pk_add_f32 v[8:9], v[8:9], v[18:19]
	v_pk_add_f32 v[6:7], v[6:7], v[20:21]
	s_waitcnt vmcnt(0)
; __device__ __forceinline__ float bf_lo(unsigned w) { return __uint_as_float(w << 16); }
; __device__ __forceinline__ float bf_hi(unsigned w) { return __uint_as_float(w & 0xffff0000u); }
; __device__ __forceinline__ unsigned pk2(float lo, float hi) { return pg8::cvt_pk_bf16(lo, hi); }
; template <int MODE> __device__ __forceinline__ void fix_resid(const float* part, int nsl, const float* xp, const float* xs, const float* meta, float* xbuf, bf16_t* xb, float* ss, float* out, int gw, int ngw, int lane) {
;     ...
;         for (int s = 0; s < nsl; ++s) { const u32x2_t w = __builtin_nontemporal_load((const u32x2_t*)(p + (size_t)s * (256 * 2048))); v += (f32x4_t){bf_lo(w.x), bf_hi(w.x), bf_lo(w.y), bf_hi(w.y)}; }
;         const float scale = (MODE == 1) ? 1.0f : 0.5f;
;         const u32x2_t bw = *(const u32x2_t*)(xb + (size_t)row * DM + col);
;         const f32x4_t o = (f32x4_t){bf_lo(bw.x), bf_hi(bw.x), bf_lo(bw.y), bf_hi(bw.y)} + v * scale;
;         if (MODE == 2) { float* dst = y_row(out, row); if (dst) __builtin_nontemporal_store(o, (f32x4_t*)(dst + col)); }
;         else {
;             u32x2_t w; w.x = pk2(o.x, o.y); w.y = pk2(o.z, o.w); *(u32x2_t*)(xb + (size_t)row * DM + col) = w;
;             const float sq = wave_sum((o.x * o.x + o.y * o.y) + (o.z * o.z + o.w * o.w));
;             if (lane == 0) __hip_atomic_fetch_add(ss + row, sq, __ATOMIC_RELAXED, __HIP_MEMORY_SCOPE_AGENT);
;         }
	v_lshlrev_b32_e32 v20, 16, v80
	v_and_b32_e32 v21, 0xffff0000, v80
	v_lshlrev_b32_e32 v18, 16, v81
	v_and_b32_e32 v19, 0xffff0000, v81
	v_pk_add_f32 v[8:9], v[8:9], v[18:19]
	v_pk_add_f32 v[6:7], v[6:7], v[20:21]
	v_lshlrev_b32_e32 v20, 16, v82
	v_and_b32_e32 v21, 0xffff0000, v82
	v_lshlrev_b32_e32 v18, 16, v83
	v_and_b32_e32 v19, 0xffff0000, v83
	v_pk_add_f32 v[8:9], v[8:9], v[18:19]
	v_pk_add_f32 v[6:7], v[6:7], v[20:21]
	v_lshlrev_b32_e32 v20, 16, v84
	v_and_b32_e32 v21, 0xffff0000, v84
	v_lshlrev_b32_e32 v18, 16, v85
	v_and_b32_e32 v19, 0xffff0000, v85
	v_pk_add_f32 v[8:9], v[8:9], v[18:19]
	v_pk_add_f32 v[6:7], v[6:7], v[20:21]
	v_lshlrev_b32_e32 v20, 16, v86
	v_and_b32_e32 v21, 0xffff0000, v86
	v_lshlrev_b32_e32 v18, 16, v87
	v_and_b32_e32 v19, 0xffff0000, v87
	v_pk_add_f32 v[8:9], v[8:9], v[18:19]
	v_pk_add_f32 v[6:7], v[6:7], v[20:21]
	v_lshlrev_b32_e32 v20, 16, v88
	v_and_b32_e32 v21, 0xffff0000, v88
	v_lshlrev_b32_e32 v18, 16, v89
	v_and_b32_e32 v19, 0xffff0000, v89
	v_pk_add_f32 v[8:9], v[8:9], v[18:19]
	v_pk_add_f32 v[6:7], v[6:7], v[20:21]
	v_lshlrev_b32_e32 v20, 16, v90
	v_and_b32_e32 v21, 0xffff0000, v90
	v_lshlrev_b32_e32 v18, 16, v91
	v_and_b32_e32 v19, 0xffff0000, v91
	v_pk_add_f32 v[8:9], v[8:9], v[18:19]
	v_pk_add_f32 v[6:7], v[6:7], v[20:21]
	v_lshlrev_b32_e32 v20, 16, v92
	v_and_b32_e32 v21, 0xffff0000, v92
	v_lshlrev_b32_e32 v18, 16, v93
	v_and_b32_e32 v19, 0xffff0000, v93
	v_pk_add_f32 v[8:9], v[8:9], v[18:19]
	v_pk_add_f32 v[6:7], v[6:7], v[20:21]
	v_lshlrev_b32_e32 v20, 16, v94
	v_and_b32_e32 v21, 0xffff0000, v94
	v_lshlrev_b32_e32 v18, 16, v95
	v_and_b32_e32 v19, 0xffff0000, v95
	v_pk_add_f32 v[8:9], v[8:9], v[18:19]
	v_pk_add_f32 v[6:7], v[6:7], v[20:21]
	s_lshl_b32 s7, s14, 8
	s_and_b32 s7, s7, 0x700
	s_addk_i32 s6, 0x2000
	v_or_b32_e32 v0, s7, v241
	s_ashr_i32 s7, s6, 31
	s_lshl_b64 s[18:19], s[6:7], 12
	s_add_u32 s18, s96, s18
	s_addc_u32 s19, s97, s19
	v_lshlrev_b32_e32 v0, 1, v0
	global_load_dwordx2 v[2:3], v0, s[18:19]
	v_cmp_lt_i32_e32 vcc, v12, v11
	s_waitcnt vmcnt(0)
	v_lshlrev_b32_e32 v4, 16, v2
	v_and_b32_e32 v5, 0xffff0000, v2
	v_lshlrev_b32_e32 v2, 16, v3
	v_and_b32_e32 v3, 0xffff0000, v3
	v_pk_fma_f32 v[2:3], v[8:9], 0.5, v[2:3] op_sel_hi:[1,0,1]
	v_pk_fma_f32 v[4:5], v[6:7], 0.5, v[4:5] op_sel_hi:[1,0,1]
	s_nop 0
	v_cvt_pk_bf16_f32 v6, v4, v5
	v_cvt_pk_bf16_f32 v7, v2, v3
	global_store_dwordx2 v0, v[6:7], s[18:19] sc0 sc1
	v_mul_f32_e32 v0, v5, v5
	v_mul_f32_e32 v3, v3, v3
	v_fmac_f32_e32 v0, v4, v4
	v_fmac_f32_e32 v3, v2, v2
	v_cndmask_b32_e32 v2, v10, v12, vcc
	v_add_f32_e32 v0, v0, v3
	v_lshlrev_b32_e32 v2, 2, v2
	ds_bpermute_b32 v2, v2, v0
	v_cmp_lt_i32_e32 vcc, v13, v11
	s_waitcnt lgkmcnt(0)
	v_add_f32_e32 v0, v0, v2
	v_cndmask_b32_e32 v2, v10, v13, vcc
	v_lshlrev_b32_e32 v2, 2, v2
	ds_bpermute_b32 v2, v2, v0
	v_cmp_lt_i32_e32 vcc, v14, v11
	s_waitcnt lgkmcnt(0)
	v_add_f32_e32 v0, v0, v2
	v_cndmask_b32_e32 v2, v10, v14, vcc
	v_lshlrev_b32_e32 v2, 2, v2
	ds_bpermute_b32 v2, v2, v0
	v_cmp_lt_i32_e32 vcc, v15, v11
	s_waitcnt lgkmcnt(0)
	v_add_f32_e32 v0, v0, v2
	v_cndmask_b32_e32 v2, v10, v15, vcc
	v_lshlrev_b32_e32 v2, 2, v2
	ds_bpermute_b32 v2, v2, v0
	v_cmp_lt_i32_e32 vcc, v16, v11
	s_waitcnt lgkmcnt(0)
	v_add_f32_e32 v0, v0, v2
	v_cndmask_b32_e32 v2, v10, v16, vcc
	v_lshlrev_b32_e32 v2, 2, v2
	ds_bpermute_b32 v2, v2, v0
	v_cmp_lt_i32_e32 vcc, v17, v11
	s_waitcnt lgkmcnt(0)
	v_add_f32_e32 v0, v0, v2
	v_cndmask_b32_e32 v2, v10, v17, vcc
	v_lshlrev_b32_e32 v2, 2, v2
	ds_bpermute_b32 v2, v2, v0
	s_mov_b64 s[18:19], exec
	v_readlane_b32 s20, v251, 31
	v_readlane_b32 s21, v251, 32
	s_and_b64 s[20:21], s[18:19], s[20:21]
	s_mov_b64 exec, s[20:21]
	s_cbranch_execz .LBB0_444
	s_mov_b64 s[20:21], exec
	s_waitcnt lgkmcnt(0)
	v_add_f32_e32 v2, v0, v2
	v_bfrev_b32_e32 v0, 1

; #define SEAM(k) do { if (IN(k) && IN((k) + 1)) { if (FLAT_BARRIER) flat_barrier((unsigned*)(ws + WS_BAR) + 64); else xcd_barrier(bar); } } while (0)
; __device__ __forceinline__ void xcd_barrier(const XcdBarrier& b) {
;     asm volatile("s_waitcnt vmcnt(0)" ::: "memory");
;     __syncthreads();
;     if (threadIdx.x == 0) {
;         unsigned* bar = b.bar;
;         __builtin_amdgcn_s_waitcnt(0);
;         unsigned nloc = b.st[0], nx = b.st[1];
;         if (nloc == 0u) { xcd_barrier_complete(bar, b.x, nloc, nx); b.st[0] = nloc; b.st[1] = nx; }
; __global__ void __launch_bounds__(NWAVES * 64, 2) fwd_megakernel(Args args) {
;     ...
;     SEAM(3);
.LBB0_452:
	s_cmp_gt_i32 s67, 4
	s_cselect_b64 s[18:19], -1, 0
	s_and_b64 s[0:1], s[0:1], s[18:19]
	s_andn2_b64 vcc, exec, s[0:1]
	s_cbranch_vccnz .LBB0_506
	s_waitcnt vmcnt(0) lgkmcnt(0)
	s_barrier
	s_mov_b64 s[98:99], exec
	v_readlane_b32 s100, v251, 27
	v_readlane_b32 s101, v251, 28
	s_and_b64 s[100:101], s[98:99], s[100:101]
	s_mov_b64 exec, s[100:101]
	s_cbranch_execz .Lsig3_done
	s_add_u32 s100, s90, 0x3700
	s_addc_u32 s101, s91, 0
	v_mov_b32_e32 v16, 0
	v_mov_b32_e32 v0, 1
	global_atomic_add v16, v0, s[100:101]
.Lsig3_done:
	s_mov_b64 exec, s[98:99]
	s_branch .LBB0_506
	s_waitcnt vmcnt(0)
	s_waitcnt vmcnt(0) lgkmcnt(0)
	s_barrier
	s_mov_b64 s[0:1], exec
	v_readlane_b32 s6, v251, 27
	v_readlane_b32 s7, v251, 28
	s_and_b64 s[6:7], s[0:1], s[6:7]
	s_mov_b64 exec, s[6:7]
	s_cbranch_execz .LBB0_505
	s_add_i32 s2, 0, 0x21000
	v_mov_b32_e32 v0, s2
	s_waitcnt vmcnt(0) expcnt(0) lgkmcnt(0)
	ds_read_b32 v2, v0
	s_add_i32 s2, 0, 0x21004
	v_mov_b32_e32 v0, s2
	ds_read_b32 v0, v0
	s_waitcnt lgkmcnt(1)
	v_cmp_ne_u32_e32 vcc, 0, v2
	s_cbranch_vccnz .LBB0_469
	v_readlane_b32 s6, v251, 0
	v_readlane_b32 s7, v251, 1
	s_load_dwordx2 s[12:13], s[6:7], 0x4
	s_add_u32 s6, s90, 0x1000
	s_addc_u32 s7, s91, 0
	s_add_u32 s20, s90, 0x1100
	s_addc_u32 s21, s91, 0
	s_add_u32 s22, s90, 0x1200
	s_addc_u32 s23, s91, 0
	s_waitcnt lgkmcnt(0)
	s_mul_i32 s2, s12, s3
	s_add_u32 s24, s90, 0x1300
	s_mul_i32 s2, s2, s13
	s_addc_u32 s25, s91, 0
	s_mov_b32 s10, 1
	v_mov_b32_e32 v16, 0
	s_branch .LBB0_457

; template <class Epi, class Sched, bool ALIGN_EPI = false, bool SP2 = false>
; __device__ __forceinline__ void gemm_phase(PG8_LAS unsigned char* lds, const Gemm g, const Sched& S, const Epi& E) {
;     ...
;         const bool has_next = S.next(ui + 1, nxt);
;         const char* nA = has_next ? (const char*)g.A + (size_t)nxt.pm * tstep + (size_t)nxt.k0 * kstepA : cA; const char* nB = has_next ? (const char*)g.Bt + (size_t)nxt.pn * tstep + (size_t)nxt.k0 * kstepB : cB;
;         for (int t = 0; t < nt; t += 2) {
;             const bool last = (t == nt - 2);
;             const char* a1 = cA + (size_t)(t + 1) * kstepA;
;             const char* a2 = last ? nA : cA + (size_t)(t + 2) * kstepA; const char* b2 = last ? nB : cB + (size_t)(t + 2) * kstepB;
;     ...
;         for (int a = 0; a < 2; ++a)
; #pragma unroll
;             for (int b = 0; b < 2; ++b)
; #pragma unroll
;                 for (int m = 0; m < 4; ++m)
; #pragma unroll
;                     for (int n = 0; n < 2; ++n) acc[a][b][m][n] = (f32x4){0.f, 0.f, 0.f, 0.f};
.LBB0_615:
	s_cmp_lg_u32 s26, 32
	s_cbranch_scc1 .Ldep4_ok
	s_add_u32 s100, s90, 0x3700
	s_addc_u32 s101, s91, 0
	v_mov_b32_e32 v1, 0
.Ldep4_spin:
	global_load_dword v0, v1, s[100:101] sc1
	s_waitcnt vmcnt(0)
	v_readfirstlane_b32 s98, v0
	s_cmpk_lt_u32 s98, 0x100
	s_cbranch_scc0 .Ldep4_got
	s_sleep 2
	s_branch .Ldep4_spin
.Ldep4_got:
	buffer_inv sc1
.Ldep4_ok:
	s_ashr_i32 s27, s26, 31
	s_lshl_b64 s[30:31], s[26:27], 20
	s_add_u32 s30, s96, s30
	s_addc_u32 s31, s97, s31
	s_and_b64 s[34:35], s[28:29], exec
	s_cselect_b32 s1, s31, s41
	s_cselect_b32 s27, s30, s40
	s_ashr_i32 s25, s24, 31
	s_lshl_b64 s[34:35], s[24:25], 20
	s_add_u32 s34, s10, s34
	s_addc_u32 s35, s12, s35
	s_and_b64 s[42:43], s[28:29], exec
	s_cselect_b32 s25, s35, s39
	s_cselect_b32 s37, s34, s38
	s_add_u32 s53, s38, 0x10000
	s_addc_u32 s54, s39, 0
	s_add_u32 s38, s40, 0x80080
	v_mov_b32_e32 v0, 0
	s_addc_u32 s39, s41, 0
	s_mov_b32 s55, -2
	v_mov_b32_e32 v1, v0
	v_mov_b32_e32 v2, v0
	v_mov_b32_e32 v3, v0
	v_mov_b32_e32 v4, v0
	v_mov_b32_e32 v5, v0
	v_mov_b32_e32 v6, v0
	v_mov_b32_e32 v7, v0
	v_mov_b32_e32 v16, v0
	v_mov_b32_e32 v17, v0
	v_mov_b32_e32 v18, v0
	v_mov_b32_e32 v19, v0
	v_mov_b32_e32 v20, v0
	v_mov_b32_e32 v21, v0
	v_mov_b32_e32 v22, v0
	v_mov_b32_e32 v23, v0
	v_mov_b32_e32 v32, v0
	v_mov_b32_e32 v33, v0
	v_mov_b32_e32 v34, v0
	v_mov_b32_e32 v35, v0
	v_mov_b32_e32 v36, v0
	v_mov_b32_e32 v37, v0
	v_mov_b32_e32 v38, v0
	v_mov_b32_e32 v39, v0
	v_mov_b32_e32 v48, v0
	v_mov_b32_e32 v49, v0
	v_mov_b32_e32 v50, v0
	v_mov_b32_e32 v51, v0
	v_mov_b32_e32 v52, v0
	v_mov_b32_e32 v53, v0
	v_mov_b32_e32 v54, v0
	v_mov_b32_e32 v55, v0
	v_mov_b32_e32 v8, v0
	v_mov_b32_e32 v9, v0
	v_mov_b32_e32 v10, v0
	v_mov_b32_e32 v11, v0
	v_mov_b32_e32 v12, v0
	v_mov_b32_e32 v13, v0
	v_mov_b32_e32 v14, v0
	v_mov_b32_e32 v15, v0
	v_mov_b32_e32 v24, v0
	v_mov_b32_e32 v25, v0
	v_mov_b32_e32 v26, v0
	v_mov_b32_e32 v27, v0
	v_mov_b32_e32 v28, v0
	v_mov_b32_e32 v29, v0
	v_mov_b32_e32 v30, v0
	v_mov_b32_e32 v31, v0
	v_mov_b32_e32 v40, v0
	v_mov_b32_e32 v41, v0
	v_mov_b32_e32 v42, v0
	v_mov_b32_e32 v43, v0
	v_mov_b32_e32 v44, v0
	v_mov_b32_e32 v45, v0
	v_mov_b32_e32 v46, v0
	v_mov_b32_e32 v47, v0
	v_mov_b32_e32 v56, v0
	v_mov_b32_e32 v57, v0
	v_mov_b32_e32 v58, v0
	v_mov_b32_e32 v59, v0
	v_mov_b32_e32 v60, v0
	v_mov_b32_e32 v61, v0
	v_mov_b32_e32 v62, v0
	v_mov_b32_e32 v63, v0
	v_mov_b32_e32 v64, v0
	v_mov_b32_e32 v65, v0
	v_mov_b32_e32 v66, v0
	v_mov_b32_e32 v67, v0
	v_mov_b32_e32 v68, v0
	v_mov_b32_e32 v69, v0
	v_mov_b32_e32 v70, v0
	v_mov_b32_e32 v71, v0
	v_mov_b32_e32 v80, v0
	v_mov_b32_e32 v81, v0
	v_mov_b32_e32 v82, v0
	v_mov_b32_e32 v83, v0
	v_mov_b32_e32 v84, v0
	v_mov_b32_e32 v85, v0
	v_mov_b32_e32 v86, v0
	v_mov_b32_e32 v87, v0
	v_mov_b32_e32 v96, v0
	v_mov_b32_e32 v97, v0
	v_mov_b32_e32 v98, v0
	v_mov_b32_e32 v99, v0
	v_mov_b32_e32 v100, v0
	v_mov_b32_e32 v101, v0
	v_mov_b32_e32 v102, v0
	v_mov_b32_e32 v103, v0
	v_mov_b32_e32 v112, v0
	v_mov_b32_e32 v113, v0
	v_mov_b32_e32 v114, v0
	v_mov_b32_e32 v115, v0
	v_mov_b32_e32 v116, v0
	v_mov_b32_e32 v117, v0
	v_mov_b32_e32 v118, v0
	v_mov_b32_e32 v119, v0
	v_mov_b32_e32 v72, v0
	v_mov_b32_e32 v73, v0
	v_mov_b32_e32 v74, v0
	v_mov_b32_e32 v75, v0
	v_mov_b32_e32 v76, v0
	v_mov_b32_e32 v77, v0
	v_mov_b32_e32 v78, v0
	v_mov_b32_e32 v79, v0
	v_mov_b32_e32 v88, v0
	v_mov_b32_e32 v89, v0
	v_mov_b32_e32 v90, v0
	v_mov_b32_e32 v91, v0
	v_mov_b32_e32 v92, v0
	v_mov_b32_e32 v93, v0
	v_mov_b32_e32 v94, v0
	v_mov_b32_e32 v95, v0
	v_mov_b32_e32 v104, v0
	v_mov_b32_e32 v105, v0
	v_mov_b32_e32 v106, v0
	v_mov_b32_e32 v107, v0
	v_mov_b32_e32 v108, v0
	v_mov_b32_e32 v109, v0
	v_mov_b32_e32 v110, v0
	v_mov_b32_e32 v111, v0
	v_mov_b32_e32 v120, v0
	v_mov_b32_e32 v121, v0
	v_mov_b32_e32 v122, v0
	v_mov_b32_e32 v123, v0
	v_mov_b32_e32 v124, v0
	v_mov_b32_e32 v125, v0
	v_mov_b32_e32 v126, v0
	v_mov_b32_e32 v127, v0

; __device__ __forceinline__ float bf_lo(unsigned w) { return __uint_as_float(w << 16); }
; __device__ __forceinline__ float bf_hi(unsigned w) { return __uint_as_float(w & 0xffff0000u); }
; __device__ __forceinline__ unsigned pk2(float lo, float hi) { return pg8::cvt_pk_bf16(lo, hi); }
; template <int MODE> __device__ __forceinline__ void fix_resid(const float* part, int nsl, const float* xp, const float* xs, const float* meta, float* xbuf, bf16_t* xb, float* ss, float* out, int gw, int ngw, int lane) {
;     for (int it = gw; it < NTAIL * 8; it += ngw) {
;         const int rloc = it >> 3, row = TAIL0 + rloc, col = (it & 7) * 256 + lane * 4;
;         const bf16_t* p = (const bf16_t*)part + (size_t)rloc * 2048 + col;
;         f32x4_t v = (f32x4_t){0.f, 0.f, 0.f, 0.f};
; #pragma unroll 8
;         for (int s = 0; s < nsl; ++s) { const u32x2_t w = __builtin_nontemporal_load((const u32x2_t*)(p + (size_t)s * (256 * 2048))); v += (f32x4_t){bf_lo(w.x), bf_hi(w.x), bf_lo(w.y), bf_hi(w.y)}; }
;         const float scale = (MODE == 1) ? 1.0f : 0.5f;
;         const u32x2_t bw = *(const u32x2_t*)(xb + (size_t)row * DM + col);
;         const f32x4_t o = (f32x4_t){bf_lo(bw.x), bf_hi(bw.x), bf_lo(bw.y), bf_hi(bw.y)} + v * scale;
;         if (MODE == 2) { float* dst = y_row(out, row); if (dst) __builtin_nontemporal_store(o, (f32x4_t*)(dst + col)); }
;         else {
;             u32x2_t w; w.x = pk2(o.x, o.y); w.y = pk2(o.z, o.w); *(u32x2_t*)(xb + (size_t)row * DM + col) = w;
;             const float sq = wave_sum((o.x * o.x + o.y * o.y) + (o.z * o.z + o.w * o.w));
;             if (lane == 0) __hip_atomic_fetch_add(ss + row, sq, __ATOMIC_RELAXED, __HIP_MEMORY_SCOPE_AGENT);
;         }
.LBB0_1199:
	v_lshl_add_u64 v[16:17], v[6:7], 0, s[8:9]
	v_add_co_u32_e32 v20, vcc, s12, v16
	global_load_dwordx2 v[18:19], v[16:17], off nt
	s_nop 0
	v_addc_co_u32_e32 v21, vcc, 0, v17, vcc
	v_add_co_u32_e32 v22, vcc, s13, v16
	s_add_u32 s8, s8, 0x800000
	s_nop 0
	v_addc_co_u32_e32 v23, vcc, 0, v17, vcc
	v_add_co_u32_e32 v24, vcc, s14, v16
	s_addc_u32 s9, s9, 0
	s_nop 0
	v_addc_co_u32_e32 v25, vcc, 0, v17, vcc
	v_add_co_u32_e32 v26, vcc, s15, v16
	s_cmp_eq_u32 s8, 0x1000000
	s_nop 0
	v_addc_co_u32_e32 v27, vcc, 0, v17, vcc
	v_add_co_u32_e32 v28, vcc, s18, v16
	s_waitcnt vmcnt(0)
	v_lshlrev_b32_e32 v32, 16, v18
	v_addc_co_u32_e32 v29, vcc, 0, v17, vcc
	v_add_co_u32_e32 v30, vcc, s19, v16
	v_and_b32_e32 v33, 0xffff0000, v18
	s_nop 0
	v_addc_co_u32_e32 v31, vcc, 0, v17, vcc
	v_add_co_u32_e32 v16, vcc, s20, v16
	v_lshlrev_b32_e32 v18, 16, v19
	s_nop 0
	v_addc_co_u32_e32 v17, vcc, 0, v17, vcc
	global_load_dwordx2 v[20:21], v[20:21], off nt
	s_nop 0
	global_load_dwordx2 v[22:23], v[22:23], off nt
	s_nop 0
	global_load_dwordx2 v[24:25], v[24:25], off nt
	s_nop 0
	global_load_dwordx2 v[26:27], v[26:27], off nt
	s_nop 0
	global_load_dwordx2 v[28:29], v[28:29], off nt
	s_nop 0
	global_load_dwordx2 v[30:31], v[30:31], off nt
	s_nop 0
	global_load_dwordx2 v[16:17], v[16:17], off nt
	v_and_b32_e32 v19, 0xffff0000, v19
	v_pk_add_f32 v[2:3], v[2:3], v[32:33]
	v_pk_add_f32 v[4:5], v[4:5], v[18:19]
	s_waitcnt vmcnt(6)
	v_lshlrev_b32_e32 v18, 16, v20
	v_and_b32_e32 v19, 0xffff0000, v20
	v_lshlrev_b32_e32 v20, 16, v21
	v_and_b32_e32 v21, 0xffff0000, v21
	s_waitcnt vmcnt(5)
	v_lshlrev_b32_e32 v32, 16, v22
	v_and_b32_e32 v33, 0xffff0000, v22
	v_lshlrev_b32_e32 v22, 16, v23
	v_and_b32_e32 v23, 0xffff0000, v23
	v_pk_add_f32 v[4:5], v[4:5], v[20:21]
	v_pk_add_f32 v[2:3], v[2:3], v[18:19]
	s_waitcnt vmcnt(4)
	v_lshlrev_b32_e32 v34, 16, v24
	v_and_b32_e32 v35, 0xffff0000, v24
	v_lshlrev_b32_e32 v24, 16, v25
	v_and_b32_e32 v25, 0xffff0000, v25
	v_pk_add_f32 v[2:3], v[2:3], v[32:33]
	v_pk_add_f32 v[4:5], v[4:5], v[22:23]
	s_waitcnt vmcnt(3)
	v_lshlrev_b32_e32 v36, 16, v26
	v_and_b32_e32 v37, 0xffff0000, v26
	v_lshlrev_b32_e32 v26, 16, v27
	v_and_b32_e32 v27, 0xffff0000, v27
	v_pk_add_f32 v[4:5], v[4:5], v[24:25]
	v_pk_add_f32 v[2:3], v[2:3], v[34:35]
	s_waitcnt vmcnt(2)
	v_lshlrev_b32_e32 v38, 16, v28
	v_and_b32_e32 v39, 0xffff0000, v28
	v_lshlrev_b32_e32 v28, 16, v29
	v_and_b32_e32 v29, 0xffff0000, v29
	v_pk_add_f32 v[2:3], v[2:3], v[36:37]
	v_pk_add_f32 v[4:5], v[4:5], v[26:27]
	s_waitcnt vmcnt(1)
	v_lshlrev_b32_e32 v40, 16, v30
	v_and_b32_e32 v41, 0xffff0000, v30
	v_lshlrev_b32_e32 v30, 16, v31
	v_and_b32_e32 v31, 0xffff0000, v31
	v_pk_add_f32 v[4:5], v[4:5], v[28:29]
	v_pk_add_f32 v[2:3], v[2:3], v[38:39]
	s_waitcnt vmcnt(0)
	v_lshlrev_b32_e32 v42, 16, v16
	v_and_b32_e32 v43, 0xffff0000, v16
	v_lshlrev_b32_e32 v16, 16, v17
	v_and_b32_e32 v17, 0xffff0000, v17
	v_pk_add_f32 v[2:3], v[2:3], v[40:41]
	v_pk_add_f32 v[4:5], v[4:5], v[30:31]
	v_pk_add_f32 v[2:3], v[2:3], v[42:43]
	v_pk_add_f32 v[4:5], v[4:5], v[16:17]
	s_cbranch_scc0 .LBB0_1199
	s_lshl_b32 s1, s21, 8
	s_and_b32 s1, s1, 0x700
	s_addk_i32 s0, 0x2000
	v_or_b32_e32 v0, s1, v241
	s_ashr_i32 s1, s0, 31
	s_lshl_b64 s[8:9], s[0:1], 12
	s_add_u32 s8, s96, s8
	s_addc_u32 s9, s97, s9
	v_lshlrev_b32_e32 v18, 1, v0
	global_load_dwordx2 v[6:7], v18, s[8:9]
	v_cmp_lt_i32_e32 vcc, v10, v9
	s_waitcnt vmcnt(0)
	v_lshlrev_b32_e32 v16, 16, v6
	v_and_b32_e32 v17, 0xffff0000, v6
	v_lshlrev_b32_e32 v6, 16, v7
	v_and_b32_e32 v7, 0xffff0000, v7
	v_pk_add_f32 v[4:5], v[4:5], v[6:7]
	v_pk_add_f32 v[6:7], v[2:3], v[16:17]
	v_mul_f32_e32 v3, v5, v5
	v_mul_f32_e32 v2, v7, v7
	v_cndmask_b32_e32 v0, v8, v10, vcc
	v_fmac_f32_e32 v2, v6, v6
	v_fmac_f32_e32 v3, v4, v4
	v_lshlrev_b32_e32 v0, 2, v0
	v_add_f32_e32 v2, v2, v3
	ds_bpermute_b32 v0, v0, v2
	v_cmp_lt_i32_e32 vcc, v11, v9
	v_cvt_pk_bf16_f32 v6, v6, v7
	v_cvt_pk_bf16_f32 v7, v4, v5
	global_store_dwordx2 v18, v[6:7], s[8:9] sc0 sc1
	s_waitcnt lgkmcnt(0)
	v_add_f32_e32 v0, v2, v0
	v_cndmask_b32_e32 v3, v8, v11, vcc
	v_lshlrev_b32_e32 v3, 2, v3
	ds_bpermute_b32 v2, v3, v0
	v_cmp_lt_i32_e32 vcc, v12, v9
	s_waitcnt lgkmcnt(0)
	v_add_f32_e32 v0, v0, v2
	v_cndmask_b32_e32 v3, v8, v12, vcc
	v_lshlrev_b32_e32 v3, 2, v3
	ds_bpermute_b32 v2, v3, v0
	v_cmp_lt_i32_e32 vcc, v13, v9
	s_waitcnt lgkmcnt(0)
	v_add_f32_e32 v0, v0, v2
	v_cndmask_b32_e32 v3, v8, v13, vcc
	v_lshlrev_b32_e32 v3, 2, v3
	ds_bpermute_b32 v2, v3, v0
	v_cmp_lt_i32_e32 vcc, v14, v9
	s_waitcnt lgkmcnt(0)
	v_add_f32_e32 v0, v0, v2
	v_cndmask_b32_e32 v3, v8, v14, vcc
	v_lshlrev_b32_e32 v3, 2, v3
	ds_bpermute_b32 v2, v3, v0
	v_cmp_lt_i32_e32 vcc, v15, v9
	s_waitcnt lgkmcnt(0)
	v_add_f32_e32 v0, v0, v2
	v_cndmask_b32_e32 v3, v8, v15, vcc
	v_lshlrev_b32_e32 v2, 2, v3
	ds_bpermute_b32 v2, v2, v0
	s_mov_b64 s[8:9], exec
	v_readlane_b32 s16, v251, 31
	v_readlane_b32 s17, v251, 32
	s_and_b64 s[16:17], s[8:9], s[16:17]
	s_mov_b64 exec, s[16:17]
	s_cbranch_execz .LBB0_1197
	s_mov_b64 s[16:17], exec
	s_waitcnt lgkmcnt(0)
	v_add_f32_e32 v2, v0, v2
	v_bfrev_b32_e32 v0, 1

; #define SEAM(k) do { if (IN(k) && IN((k) + 1)) { if (FLAT_BARRIER) flat_barrier((unsigned*)(ws + WS_BAR) + 64); else xcd_barrier(bar); } } while (0)
; __device__ __forceinline__ void xcd_barrier(const XcdBarrier& b) {
;     asm volatile("s_waitcnt vmcnt(0)" ::: "memory");
;     __syncthreads();
;     if (threadIdx.x == 0) {
;         unsigned* bar = b.bar;
;         __builtin_amdgcn_s_waitcnt(0);
;         unsigned nloc = b.st[0], nx = b.st[1];
;         if (nloc == 0u) { xcd_barrier_complete(bar, b.x, nloc, nx); b.st[0] = nloc; b.st[1] = nx; }
; __global__ void __launch_bounds__(NWAVES * 64, 2) fwd_megakernel(Args args) {
;     ...
;     SEAM(9);
.LBB0_1205:
	s_cmp_gt_i32 s67, 10
	s_cselect_b64 s[0:1], -1, 0
	s_and_b64 s[6:7], s[6:7], s[0:1]
	s_andn2_b64 vcc, exec, s[6:7]
	s_cbranch_vccnz .LBB0_1259
	s_waitcnt vmcnt(0) lgkmcnt(0)
	s_barrier
	s_mov_b64 s[98:99], exec
	v_readlane_b32 s100, v251, 27
	v_readlane_b32 s101, v251, 28
	s_and_b64 s[100:101], s[98:99], s[100:101]
	s_mov_b64 exec, s[100:101]
	s_cbranch_execz .Lsig9_done
	s_add_u32 s100, s90, 0x3900
	s_addc_u32 s101, s91, 0
	v_mov_b32_e32 v16, 0
	v_mov_b32_e32 v0, 1
	global_atomic_add v16, v0, s[100:101]
.Lsig9_done:
	s_mov_b64 exec, s[98:99]
	s_branch .LBB0_1259
	s_waitcnt vmcnt(0)
	s_waitcnt vmcnt(0) lgkmcnt(0)
	s_barrier
	s_mov_b64 s[6:7], exec
	v_readlane_b32 s8, v251, 27
	v_readlane_b32 s9, v251, 28
	s_and_b64 s[8:9], s[6:7], s[8:9]
	s_mov_b64 exec, s[8:9]
	s_cbranch_execz .LBB0_1258
	s_add_i32 s2, 0, 0x21000
	v_mov_b32_e32 v0, s2
	s_waitcnt vmcnt(0) expcnt(0) lgkmcnt(0)
	ds_read_b32 v2, v0
	s_add_i32 s2, 0, 0x21004
	v_mov_b32_e32 v0, s2
	ds_read_b32 v0, v0
	s_waitcnt lgkmcnt(1)
	v_cmp_ne_u32_e32 vcc, 0, v2
	s_cbranch_vccnz .LBB0_1222
	v_readlane_b32 s8, v251, 0
	v_readlane_b32 s9, v251, 1
	s_load_dwordx2 s[12:13], s[8:9], 0x4
	s_add_u32 s8, s90, 0x1000
	s_addc_u32 s9, s91, 0
	s_add_u32 s16, s90, 0x1100
	s_addc_u32 s17, s91, 0
	s_add_u32 s18, s90, 0x1200
	s_addc_u32 s19, s91, 0
	s_waitcnt lgkmcnt(0)
	s_mul_i32 s2, s12, s3
	s_add_u32 s20, s90, 0x1300
	s_mul_i32 s2, s2, s13
	s_addc_u32 s21, s91, 0
	s_mov_b32 s10, 1
	v_mov_b32_e32 v16, 0
	s_branch .LBB0_1210

; template <class Epi, class Sched, bool ALIGN_EPI = false, bool SP2 = false>
; __device__ __forceinline__ void gemm_phase(PG8_LAS unsigned char* lds, const Gemm g, const Sched& S, const Epi& E) {
;     ...
;     for (;;) {
;         const bool has_next = S.next(ui + 1, nxt);
;         const char* nA = has_next ? (const char*)g.A + (size_t)nxt.pm * tstep + (size_t)nxt.k0 * kstepA : cA; const char* nB = has_next ? (const char*)g.Bt + (size_t)nxt.pn * tstep + (size_t)nxt.k0 * kstepB : cB;
;         for (int t = 0; t < nt; t += 2) {
;             const bool last = (t == nt - 2);
;             const char* a1 = cA + (size_t)(t + 1) * kstepA;
;             const char* a2 = last ? nA : cA + (size_t)(t + 2) * kstepA; const char* b2 = last ? nB : cB + (size_t)(t + 2) * kstepB;
;             const char* a3 = a2 + kstepA; const char* b3 = b2 + kstepB;
;             if (last && has_next) S.a_ready(nxt);
.LBB0_1338:
	s_cmp_lg_u32 s22, 32
	s_cbranch_scc1 .Ldep10_ok
	s_add_u32 s100, s90, 0x3900
	s_addc_u32 s101, s91, 0
	v_mov_b32_e32 v1, 0

; template <class Epi, class Sched, bool ALIGN_EPI = false, bool SP2 = false>
; __device__ __forceinline__ void gemm_phase(PG8_LAS unsigned char* lds, const Gemm g, const Sched& S, const Epi& E) {
;     ...
;         const bool has_next = S.next(ui + 1, nxt);
;         const char* nA = has_next ? (const char*)g.A + (size_t)nxt.pm * tstep + (size_t)nxt.k0 * kstepA : cA; const char* nB = has_next ? (const char*)g.Bt + (size_t)nxt.pn * tstep + (size_t)nxt.k0 * kstepB : cB;
;         for (int t = 0; t < nt; t += 2) {
;             const bool last = (t == nt - 2);
;             const char* a1 = cA + (size_t)(t + 1) * kstepA;
;             const char* a2 = last ? nA : cA + (size_t)(t + 2) * kstepA; const char* b2 = last ? nB : cB + (size_t)(t + 2) * kstepB;
;     ...
;         for (int a = 0; a < 2; ++a)
; #pragma unroll
;             for (int b = 0; b < 2; ++b)
; #pragma unroll
;                 for (int m = 0; m < 4; ++m)
; #pragma unroll
;                     for (int n = 0; n < 2; ++n) acc[a][b][m][n] = (f32x4){0.f, 0.f, 0.f, 0.f};
.Ldep10_got:
	buffer_inv sc1
.Ldep10_ok:
	s_ashr_i32 s23, s22, 31
	s_lshl_b64 s[26:27], s[22:23], 20
	s_add_u32 s26, s96, s26
	s_addc_u32 s27, s97, s27
	s_and_b64 s[28:29], s[24:25], exec
	s_cselect_b32 s23, s27, s37
	s_cselect_b32 s49, s26, s36
	s_ashr_i32 s21, s20, 31
	s_lshl_b64 s[28:29], s[20:21], 20
	s_add_u32 s28, s10, s28
	s_addc_u32 s29, s14, s29
	s_and_b64 s[38:39], s[24:25], exec
	s_cselect_b32 s21, s29, s35
	s_cselect_b32 s50, s28, s34
	s_add_u32 s51, s34, 0x10000
	s_addc_u32 s52, s35, 0
	s_add_u32 s34, s36, 0x80080
	v_mov_b32_e32 v0, 0
	s_addc_u32 s35, s37, 0
	s_mov_b32 s53, -2
	v_mov_b32_e32 v1, v0
	v_mov_b32_e32 v2, v0
	v_mov_b32_e32 v3, v0
	v_mov_b32_e32 v4, v0
	v_mov_b32_e32 v5, v0
	v_mov_b32_e32 v6, v0
	v_mov_b32_e32 v7, v0
	v_mov_b32_e32 v16, v0
	v_mov_b32_e32 v17, v0
	v_mov_b32_e32 v18, v0
	v_mov_b32_e32 v19, v0
	v_mov_b32_e32 v20, v0
	v_mov_b32_e32 v21, v0
	v_mov_b32_e32 v22, v0
	v_mov_b32_e32 v23, v0
	v_mov_b32_e32 v32, v0
	v_mov_b32_e32 v33, v0
	v_mov_b32_e32 v34, v0
	v_mov_b32_e32 v35, v0
	v_mov_b32_e32 v36, v0
	v_mov_b32_e32 v37, v0
	v_mov_b32_e32 v38, v0
	v_mov_b32_e32 v39, v0
	v_mov_b32_e32 v48, v0
	v_mov_b32_e32 v49, v0
	v_mov_b32_e32 v50, v0
	v_mov_b32_e32 v51, v0
	v_mov_b32_e32 v52, v0
	v_mov_b32_e32 v53, v0
	v_mov_b32_e32 v54, v0
	v_mov_b32_e32 v55, v0
	v_mov_b32_e32 v8, v0
	v_mov_b32_e32 v9, v0
	v_mov_b32_e32 v10, v0
	v_mov_b32_e32 v11, v0
	v_mov_b32_e32 v12, v0
	v_mov_b32_e32 v13, v0
	v_mov_b32_e32 v14, v0
	v_mov_b32_e32 v15, v0
	v_mov_b32_e32 v24, v0
	v_mov_b32_e32 v25, v0
	v_mov_b32_e32 v26, v0
	v_mov_b32_e32 v27, v0
	v_mov_b32_e32 v28, v0
	v_mov_b32_e32 v29, v0
	v_mov_b32_e32 v30, v0
	v_mov_b32_e32 v31, v0
	v_mov_b32_e32 v40, v0
	v_mov_b32_e32 v41, v0
	v_mov_b32_e32 v42, v0
	v_mov_b32_e32 v43, v0
	v_mov_b32_e32 v44, v0
	v_mov_b32_e32 v45, v0
	v_mov_b32_e32 v46, v0
	v_mov_b32_e32 v47, v0
	v_mov_b32_e32 v56, v0
	v_mov_b32_e32 v57, v0
	v_mov_b32_e32 v58, v0
	v_mov_b32_e32 v59, v0
	v_mov_b32_e32 v60, v0
	v_mov_b32_e32 v61, v0
	v_mov_b32_e32 v62, v0
	v_mov_b32_e32 v63, v0
	v_mov_b32_e32 v64, v0
	v_mov_b32_e32 v65, v0
	v_mov_b32_e32 v66, v0
	v_mov_b32_e32 v67, v0
	v_mov_b32_e32 v68, v0
	v_mov_b32_e32 v69, v0
	v_mov_b32_e32 v70, v0
	v_mov_b32_e32 v71, v0
	v_mov_b32_e32 v80, v0
	v_mov_b32_e32 v81, v0
	v_mov_b32_e32 v82, v0
	v_mov_b32_e32 v83, v0
	v_mov_b32_e32 v84, v0
	v_mov_b32_e32 v85, v0
	v_mov_b32_e32 v86, v0
	v_mov_b32_e32 v87, v0
	v_mov_b32_e32 v96, v0
	v_mov_b32_e32 v97, v0
	v_mov_b32_e32 v98, v0
	v_mov_b32_e32 v99, v0
	v_mov_b32_e32 v100, v0
	v_mov_b32_e32 v101, v0
	v_mov_b32_e32 v102, v0
	v_mov_b32_e32 v103, v0
	v_mov_b32_e32 v112, v0
	v_mov_b32_e32 v113, v0
	v_mov_b32_e32 v114, v0
	v_mov_b32_e32 v115, v0
	v_mov_b32_e32 v116, v0
	v_mov_b32_e32 v117, v0
	v_mov_b32_e32 v118, v0
	v_mov_b32_e32 v119, v0
	v_mov_b32_e32 v72, v0
	v_mov_b32_e32 v73, v0
	v_mov_b32_e32 v74, v0
	v_mov_b32_e32 v75, v0
	v_mov_b32_e32 v76, v0
	v_mov_b32_e32 v77, v0
	v_mov_b32_e32 v78, v0
	v_mov_b32_e32 v79, v0
	v_mov_b32_e32 v88, v0
	v_mov_b32_e32 v89, v0
	v_mov_b32_e32 v90, v0
	v_mov_b32_e32 v91, v0
	v_mov_b32_e32 v92, v0
	v_mov_b32_e32 v93, v0
	v_mov_b32_e32 v94, v0
	v_mov_b32_e32 v95, v0
	v_mov_b32_e32 v104, v0
	v_mov_b32_e32 v105, v0
	v_mov_b32_e32 v106, v0
	v_mov_b32_e32 v107, v0
	v_mov_b32_e32 v108, v0
	v_mov_b32_e32 v109, v0
	v_mov_b32_e32 v110, v0
	v_mov_b32_e32 v111, v0
	v_mov_b32_e32 v120, v0
	v_mov_b32_e32 v121, v0
	v_mov_b32_e32 v122, v0
	v_mov_b32_e32 v123, v0
	v_mov_b32_e32 v124, v0
	v_mov_b32_e32 v125, v0
	v_mov_b32_e32 v126, v0
	v_mov_b32_e32 v127, v0
